# mix0 dynamic queue: gmlp tiles spread evenly (8 attention : 3 gmlp) through all attention tiles, last 256 gmlp tiles as tail
# speedup vs baseline: 1.0085x; 1.0085x over previous
.Lmy_m0_map:
	s_cmpk_lt_i32 s93, 0xc00
	s_cbranch_scc0 .LBB0_261
	s_mov_b32 s88, s93
	s_cmpk_ge_i32 s93, 0xb00
	s_cbranch_scc1 .Lmy_m0_mapped
	s_mul_i32 s98, s93, 0x1746
	s_lshr_b32 s98, s98, 16
	s_mul_i32 s100, s98, 11
	s_sub_i32 s100, s93, s100
	s_lshl_b32 s88, s98, 3
	s_add_i32 s88, s88, s100
	s_cmp_gt_u32 s100, 3
	s_cselect_b32 s94, 1, 0
	s_sub_i32 s88, s88, s94
	s_cmp_gt_u32 s100, 7
	s_cselect_b32 s94, 1, 0
	s_sub_i32 s88, s88, s94
	s_mul_i32 s98, s98, 3
	s_add_i32 s98, s98, 0x800
	s_cmp_eq_u32 s100, 3
	s_cselect_b32 s88, s98, s88
	s_add_i32 s98, s98, 1
	s_cmp_eq_u32 s100, 7
	s_cselect_b32 s88, s98, s88
	s_add_i32 s98, s98, 1
	s_cmp_eq_u32 s100, 10
	s_cselect_b32 s88, s98, s88
